# FFN1/PROJ LDS-DMA loops with three LDS buffers (DMA two stages ahead, counted vmcnt) on top of the spread schedule
# baseline (speedup 1.0000x reference)
; DI int TIDX() { int t = threadIdx.x; asm volatile("" : "+v"(t)); return t; }
; #define XCD_LOOP_W(Mt, ntn) const int xcd_ = BIDX() & 7; const int Mx_ = ((Mt) + 7) >> 3; for (int u_ = BIDX() >> 3; u_ < Mx_ * (ntn); u_ += (int)(gridDim.x >> 3))
; template <class BR>
; DI void gemm_tile_w(const h16* __restrict__ A, int lda, const h16* __restrict__ B, int ldb, BR brow, int K, f32x16 (&acc)[4][2], h16* sm) {
;   const int tid = TIDX(), lane = tid & 63, w = tid >> 6, wm = w >> 1, wn = w & 1, r = lane & 31, hh = lane >> 5;
;   const unsigned ao = (unsigned)(tid >> 2) * (unsigned)lda + (unsigned)(tid & 3) * 8u;
;   const unsigned bo0 = (unsigned)brow(tid >> 2) * (unsigned)ldb + (unsigned)(tid & 3) * 8u;
;   const unsigned bo1 = (unsigned)brow((tid >> 2) + 64) * (unsigned)ldb + (unsigned)(tid & 3) * 8u;
;   const h16* ag = A;
;   const h16* bg = B;
;   u32x4 ra0[4], rb0[2], ra1[4], rb1[2];
; #pragma unroll
;   for (int i = 0; i < 4; ++i) ra0[i] = *(const u32x4*)(ag + (ao + (unsigned)i * 64u * (unsigned)lda));
;   rb0[0] = *(const u32x4*)(bg + bo0);
;   rb0[1] = *(const u32x4*)(bg + bo1);
;   ag += 32; bg += 32;
; #pragma unroll
;   for (int i = 0; i < 4; ++i) ra1[i] = *(const u32x4*)(ag + (ao + (unsigned)i * 64u * (unsigned)lda));
;   rb1[0] = *(const u32x4*)(bg + bo0);
;   rb1[1] = *(const u32x4*)(bg + bo1);
;   const int nk = K >> 5;
;   const int wofs = (tid >> 2) * LS2 + (tid & 3) * 8;
; DI void phase_ffn1(const P& p, int l, int hf, char* smem) {
;     ...
;   XCD_LOOP_W(Mt, 44) {
;     int mt_, nt_;
;     tile_map(u_, Mx_, 44, xcd_, mt_, nt_);
;     if (mt_ >= Mt) continue;
;     const int m0 = mt0 * 128 + mt_ * 256, c0 = nt_ * 64;
;     f32x16 acc[4][2];
;     zero_acc_w(acc);
;     gemm_tile_w(h2 + (size_t)m0 * 1024, 1024, W, 1024,
;                 [&](int rr) { const int q = rr & 63; return ((q >> 5) ? 2816 : 0) + c0 + (rr >> 6) * 32 + (q & 31); }, 1024, acc, (h16*)smem);
.LBB0_71:
	s_mul_hi_i32 s12, s22, 0x2e8ba2e9
	s_lshr_b32 s13, s12, 31
	s_ashr_i32 s12, s12, 6
	s_add_i32 s12, s12, s13
	s_lshl_b32 s14, s12, 3
	s_sub_i32 s13, s21, s14
	s_min_i32 s15, s13, 8
	s_abs_i32 s13, s15
	v_cvt_f32_u32_e32 v0, s13
	s_sub_i32 s18, 0, s13
	s_mulk_i32 s12, 0xfea0
	s_add_i32 s12, s12, s22
	v_rcp_iflag_f32_e32 v0, v0
	s_abs_i32 s16, s12
	s_xor_b32 s17, s12, s15
	s_ashr_i32 s17, s17, 31
	v_mul_f32_e32 v0, 0x4f7ffffe, v0
	v_cvt_u32_f32_e32 v0, v0
	s_nop 0
	v_readfirstlane_b32 s19, v0
	s_mul_i32 s18, s18, s19
	s_mul_hi_u32 s18, s19, s18
	s_add_i32 s19, s19, s18
	s_mul_hi_u32 s18, s16, s19
	s_mul_i32 s19, s18, s13
	s_sub_i32 s16, s16, s19
	s_add_i32 s26, s18, 1
	s_sub_i32 s19, s16, s13
	s_cmp_ge_u32 s16, s13
	s_cselect_b32 s18, s26, s18
	s_cselect_b32 s16, s19, s16
	s_add_i32 s19, s18, 1
	s_cmp_ge_u32 s16, s13
	s_cselect_b32 s13, s19, s18
	s_xor_b32 s13, s13, s17
	s_sub_i32 s13, s13, s17
	s_add_i32 s14, s14, s38
	s_mul_i32 s15, s15, s13
	s_add_i32 s14, s14, s12
	s_sub_i32 s12, s14, s15
	s_cmp_ge_i32 s12, s20
	s_cbranch_scc1 .LBB0_70
	v_mov_b32_e32 v18, v203
	s_lshl_b32 s26, s13, 6
	s_lshl_b32 s12, s12, 8
	v_ashrrev_i32_e32 v19, 2, v18
	v_bfe_i32 v2, v18, 7, 1
	v_and_b32_e32 v2, 0xb00, v2
	v_lshrrev_b32_e32 v3, 3, v18
	v_and_or_b32 v4, v19, 31, s26
	v_and_b32_e32 v3, 0x3fffe0, v3
	v_add_u32_e32 v2, v2, v4
	v_add_u32_e32 v10, v2, v3
	v_add_u32_e32 v3, 64, v19
	s_ashr_i32 s13, s12, 31
	v_lshlrev_b32_e32 v0, 3, v18
	v_lshrrev_b32_e32 v3, 1, v3
	s_lshl_b64 s[14:15], s[12:13], 11
	v_and_b32_e32 v20, 24, v0
	v_bfe_u32 v21, v18, 4, 2
	v_lshlrev_b32_e32 v21, 3, v21
	v_xor_b32_e32 v20, v20, v21
	v_and_b32_e32 v3, 0x3fffe0, v3
	s_add_u32 s14, s24, s14
	v_add_u32_e32 v11, v2, v3
	v_lshl_or_b32 v210, v10, 10, v20
	v_mov_b32_e32 v211, v1
	s_addc_u32 s15, s25, s15
	v_lshl_or_b32 v0, v19, 10, v20
	v_lshl_or_b32 v212, v11, 10, v20
	v_lshlrev_b64 v[10:11], 1, v[210:211]
	v_mov_b32_e32 v213, v1
	v_lshl_add_u64 v[2:3], v[0:1], 1, s[14:15]
	v_add_u32_e32 v204, 0x10000, v0
	v_mov_b32_e32 v205, v1
	v_add_u32_e32 v206, 0x20000, v0
	v_mov_b32_e32 v207, v1
	v_add_u32_e32 v208, 0x30000, v0
	v_mov_b32_e32 v209, v1
	v_lshl_add_u64 v[12:13], s[6:7], 0, v[10:11]
	v_lshlrev_b64 v[14:15], 1, v[212:213]
	v_lshl_add_u64 v[4:5], v[204:205], 1, s[14:15]
	v_lshl_add_u64 v[6:7], v[206:207], 1, s[14:15]
	v_lshl_add_u64 v[8:9], v[208:209], 1, s[14:15]
	v_lshl_add_u64 v[16:17], s[6:7], 0, v[14:15]
	v_readfirstlane_b32 s18, v203
	s_nop 3
	s_lshr_b32 s18, s18, 6
	s_lshl_b32 s18, s18, 10
	v_and_b32_e32 v136, 31, v203
	v_bfe_u32 v137, v203, 5, 1
	v_bfe_u32 v138, v203, 2, 2
	v_xor_b32_e32 v137, v137, v138
	v_lshlrev_b32_e32 v137, 4, v137
	v_lshl_or_b32 v136, v136, 6, v137
	v_lshrrev_b32_e32 v138, 7, v203
	v_lshl_add_u32 v130, v138, 13, v136
	v_bfe_u32 v138, v203, 6, 1
	v_lshl_add_u32 v132, v138, 12, v136
	v_add_u32_e32 v132, 0x4000, v132
	v_xor_b32_e32 v131, 32, v130
	v_xor_b32_e32 v133, 32, v132
	v_lshlrev_b32_e32 v139, 1, v0
	v_lshlrev_b32_e32 v140, 1, v204
	v_lshlrev_b32_e32 v141, 1, v206
	v_lshlrev_b32_e32 v142, 1, v208
	v_lshlrev_b32_e32 v143, 1, v210
	v_lshlrev_b32_e32 v144, 1, v212
	s_mov_b64 s[16:17], s[6:7]
	s_add_u32 m0, s18, 0x0
	s_nop 0
	global_load_lds_dwordx4 v139, s[14:15]
	s_add_u32 m0, s18, 0x1000
	s_nop 0
	global_load_lds_dwordx4 v140, s[14:15]
	s_add_u32 m0, s18, 0x2000
	s_nop 0
	global_load_lds_dwordx4 v141, s[14:15]
	s_add_u32 m0, s18, 0x3000
	s_nop 0
	global_load_lds_dwordx4 v142, s[14:15]
	s_add_u32 m0, s18, 0x4000
	s_nop 0
	global_load_lds_dwordx4 v143, s[16:17]
	s_add_u32 m0, s18, 0x5000
	s_nop 0
	global_load_lds_dwordx4 v144, s[16:17]
	s_add_u32 s14, s14, 64
	s_addc_u32 s15, s15, 0
	s_add_u32 s16, s16, 64
	s_addc_u32 s17, s17, 0
	s_add_u32 m0, s18, 0x6000
	s_nop 0
	global_load_lds_dwordx4 v139, s[14:15]
	s_add_u32 m0, s18, 0x7000
	s_nop 0
	global_load_lds_dwordx4 v140, s[14:15]
	s_add_u32 m0, s18, 0x8000
	s_nop 0
	global_load_lds_dwordx4 v141, s[14:15]
	s_add_u32 m0, s18, 0x9000
	s_nop 0
	global_load_lds_dwordx4 v142, s[14:15]
	s_add_u32 m0, s18, 0xa000
	s_nop 0
	global_load_lds_dwordx4 v143, s[16:17]
	s_add_u32 m0, s18, 0xb000
	s_nop 0
	global_load_lds_dwordx4 v144, s[16:17]
	s_add_u32 s14, s14, 64
	s_addc_u32 s15, s15, 0
	s_add_u32 s16, s16, 64
	s_addc_u32 s17, s17, 0
	v_mov_b32_e32 v2, 0
	s_mov_b32 s13, 0
	v_mov_b32_e32 v3, v2
	v_mov_b32_e32 v4, v2
	v_mov_b32_e32 v5, v2
	v_mov_b32_e32 v6, v2
	v_mov_b32_e32 v7, v2
	v_mov_b32_e32 v8, v2
	v_mov_b32_e32 v9, v2
	v_mov_b32_e32 v10, v2
	v_mov_b32_e32 v11, v2
	v_mov_b32_e32 v12, v2
	v_mov_b32_e32 v13, v2
	v_mov_b32_e32 v14, v2
	v_mov_b32_e32 v15, v2
	v_mov_b32_e32 v16, v2
	v_mov_b32_e32 v17, v2
	v_mov_b32_e32 v18, v2
	v_mov_b32_e32 v19, v2
	v_mov_b32_e32 v20, v2
	v_mov_b32_e32 v21, v2
	v_mov_b32_e32 v22, v2
	v_mov_b32_e32 v23, v2
	v_mov_b32_e32 v24, v2
	v_mov_b32_e32 v25, v2
	v_mov_b32_e32 v26, v2
	v_mov_b32_e32 v27, v2
	v_mov_b32_e32 v28, v2
	v_mov_b32_e32 v29, v2
	v_mov_b32_e32 v30, v2
	v_mov_b32_e32 v31, v2
	v_mov_b32_e32 v32, v2
	v_mov_b32_e32 v33, v2
	v_mov_b32_e32 v34, v2
	v_mov_b32_e32 v35, v2
	v_mov_b32_e32 v36, v2
	v_mov_b32_e32 v37, v2
	v_mov_b32_e32 v38, v2
	v_mov_b32_e32 v39, v2
	v_mov_b32_e32 v40, v2
	v_mov_b32_e32 v41, v2
	v_mov_b32_e32 v42, v2
	v_mov_b32_e32 v43, v2
	v_mov_b32_e32 v44, v2
	v_mov_b32_e32 v45, v2
	v_mov_b32_e32 v46, v2
	v_mov_b32_e32 v47, v2
	v_mov_b32_e32 v48, v2
	v_mov_b32_e32 v49, v2
	s_waitcnt vmcnt(15)
; template <class BR>
; DI void gemm_tile_w(const h16* __restrict__ A, int lda, const h16* __restrict__ B, int ldb, BR brow, int K, f32x16 (&acc)[4][2], h16* sm) {
;     ...
;   for (int kt = 0; kt < nk; kt += 2) {
;     WIDE_HALF(ra0, rb0, 0, kt)
;     WIDE_HALF(ra1, rb1, 1, kt + 1)
;   }
	v_mov_b32_e32 v50, v2
	v_mov_b32_e32 v51, v2
	v_mov_b32_e32 v52, v2
	v_mov_b32_e32 v53, v2
	s_waitcnt vmcnt(14)
	v_mov_b32_e32 v54, v2
	v_mov_b32_e32 v55, v2
	v_mov_b32_e32 v56, v2
	v_mov_b32_e32 v57, v2
	s_waitcnt vmcnt(13)
	v_mov_b32_e32 v58, v2
	v_mov_b32_e32 v59, v2
	v_mov_b32_e32 v60, v2
	v_mov_b32_e32 v61, v2
	s_waitcnt vmcnt(12)
	v_mov_b32_e32 v62, v2
	v_mov_b32_e32 v63, v2
	v_mov_b32_e32 v64, v2
	v_mov_b32_e32 v65, v2
	v_mov_b32_e32 v66, v2
	v_mov_b32_e32 v67, v2
	v_mov_b32_e32 v68, v2
	v_mov_b32_e32 v69, v2
	v_mov_b32_e32 v70, v2
	v_mov_b32_e32 v71, v2
	v_mov_b32_e32 v72, v2
	v_mov_b32_e32 v73, v2
	v_mov_b32_e32 v74, v2
	v_mov_b32_e32 v75, v2
	v_mov_b32_e32 v76, v2
	v_mov_b32_e32 v77, v2
	v_mov_b32_e32 v78, v2
	v_mov_b32_e32 v79, v2
	v_mov_b32_e32 v80, v2
	v_mov_b32_e32 v81, v2
	v_mov_b32_e32 v82, v2
	v_mov_b32_e32 v83, v2
	v_mov_b32_e32 v84, v2
	v_mov_b32_e32 v85, v2
	v_mov_b32_e32 v86, v2
	v_mov_b32_e32 v87, v2
	v_mov_b32_e32 v88, v2
	v_mov_b32_e32 v89, v2
	v_mov_b32_e32 v90, v2
	v_mov_b32_e32 v91, v2
	v_mov_b32_e32 v92, v2
	v_mov_b32_e32 v93, v2
	v_mov_b32_e32 v94, v2
	v_mov_b32_e32 v95, v2
	v_mov_b32_e32 v96, v2
	v_mov_b32_e32 v97, v2
	v_mov_b32_e32 v98, v2
	v_mov_b32_e32 v99, v2
	v_mov_b32_e32 v100, v2
	v_mov_b32_e32 v101, v2
	v_mov_b32_e32 v102, v2
	v_mov_b32_e32 v103, v2
	v_mov_b32_e32 v104, v2
	v_mov_b32_e32 v105, v2
	v_mov_b32_e32 v106, v2
	v_mov_b32_e32 v107, v2
	v_mov_b32_e32 v108, v2
	v_mov_b32_e32 v109, v2
	v_mov_b32_e32 v110, v2
	v_mov_b32_e32 v111, v2
	v_mov_b32_e32 v112, v2
	v_mov_b32_e32 v113, v2
	v_mov_b32_e32 v114, v2
	v_mov_b32_e32 v115, v2
	v_mov_b32_e32 v116, v2
	v_mov_b32_e32 v117, v2
	v_mov_b32_e32 v118, v2
	v_mov_b32_e32 v119, v2
	v_mov_b32_e32 v120, v2
	v_mov_b32_e32 v121, v2
	v_mov_b32_e32 v122, v2
	v_mov_b32_e32 v123, v2
	v_mov_b32_e32 v124, v2
	v_mov_b32_e32 v125, v2
	v_mov_b32_e32 v126, v2
	v_mov_b32_e32 v127, v2
	v_mov_b32_e32 v128, v2
	v_mov_b32_e32 v129, v2
	s_waitcnt vmcnt(6)
	s_barrier
.Lfg_stage0:
	ds_read_b128 v[178:181], v130 offset:0
	ds_read_b128 v[194:197], v132 offset:0
	ds_read_b128 v[198:201], v132 offset:2048
	ds_read_b128 v[182:185], v130 offset:2048
	ds_read_b128 v[186:189], v130 offset:4096
	ds_read_b128 v[190:193], v130 offset:6144
	s_cmp_ge_u32 s13, 30
	s_cbranch_scc1 .Lfg_nl0
	s_waitcnt lgkmcnt(4)
	v_mfma_f32_32x32x16_f16 v[114:129], v[178:181], v[194:197], v[114:129]
	ds_read_b128 v[216:219], v131 offset:0
	s_waitcnt lgkmcnt(4)
	s_add_u32 m0, s18, 0xc000
	v_mfma_f32_32x32x16_f16 v[98:113], v[178:181], v[198:201], v[98:113]
	global_load_lds_dwordx4 v139, s[14:15]
	ds_read_b128 v[234:237], v133 offset:0
	s_waitcnt lgkmcnt(4)
	s_add_u32 m0, s18, 0xd000
	v_mfma_f32_32x32x16_f16 v[82:97], v[182:185], v[194:197], v[82:97]
	global_load_lds_dwordx4 v140, s[14:15]
	ds_read_b128 v[240:243], v133 offset:2048
	s_add_u32 m0, s18, 0xe000
	v_mfma_f32_32x32x16_f16 v[66:81], v[182:185], v[198:201], v[66:81]
	global_load_lds_dwordx4 v141, s[14:15]
	ds_read_b128 v[220:223], v131 offset:2048
	s_waitcnt lgkmcnt(5)
	s_add_u32 m0, s18, 0xf000
	v_mfma_f32_32x32x16_f16 v[50:65], v[186:189], v[194:197], v[50:65]
	global_load_lds_dwordx4 v142, s[14:15]
	ds_read_b128 v[226:229], v131 offset:4096
	s_add_u32 m0, s18, 0x10000
	v_mfma_f32_32x32x16_f16 v[34:49], v[186:189], v[198:201], v[34:49]
	global_load_lds_dwordx4 v143, s[16:17]
	ds_read_b128 v[230:233], v131 offset:6144
	s_waitcnt lgkmcnt(6)
	s_add_u32 m0, s18, 0x11000
	v_mfma_f32_32x32x16_f16 v[18:33], v[190:193], v[194:197], v[18:33]
	global_load_lds_dwordx4 v144, s[16:17]
	v_mfma_f32_32x32x16_f16 v[2:17], v[190:193], v[198:201], v[2:17]
	s_add_u32 s14, s14, 64
	s_addc_u32 s15, s15, 0
	s_add_u32 s16, s16, 64
	s_addc_u32 s17, s17, 0
	s_branch .Lfg_dd0
.Lfg_nl0:
	s_waitcnt lgkmcnt(4)
	v_mfma_f32_32x32x16_f16 v[114:129], v[178:181], v[194:197], v[114:129]
	ds_read_b128 v[216:219], v131 offset:0
	s_waitcnt lgkmcnt(4)
	v_mfma_f32_32x32x16_f16 v[98:113], v[178:181], v[198:201], v[98:113]
	ds_read_b128 v[234:237], v133 offset:0
	s_waitcnt lgkmcnt(4)
	v_mfma_f32_32x32x16_f16 v[82:97], v[182:185], v[194:197], v[82:97]
	ds_read_b128 v[240:243], v133 offset:2048
	v_mfma_f32_32x32x16_f16 v[66:81], v[182:185], v[198:201], v[66:81]
	ds_read_b128 v[220:223], v131 offset:2048
	s_waitcnt lgkmcnt(5)
	v_mfma_f32_32x32x16_f16 v[50:65], v[186:189], v[194:197], v[50:65]
	ds_read_b128 v[226:229], v131 offset:4096
	v_mfma_f32_32x32x16_f16 v[34:49], v[186:189], v[198:201], v[34:49]
	ds_read_b128 v[230:233], v131 offset:6144
	s_waitcnt lgkmcnt(6)
	v_mfma_f32_32x32x16_f16 v[18:33], v[190:193], v[194:197], v[18:33]
	v_mfma_f32_32x32x16_f16 v[2:17], v[190:193], v[198:201], v[2:17]
.Lfg_dd0:
	s_waitcnt lgkmcnt(4)
	v_mfma_f32_32x32x16_f16 v[114:129], v[216:219], v[234:237], v[114:129]
	s_waitcnt lgkmcnt(3)
	v_mfma_f32_32x32x16_f16 v[98:113], v[216:219], v[240:243], v[98:113]
	s_waitcnt lgkmcnt(2)
	v_mfma_f32_32x32x16_f16 v[82:97], v[220:223], v[234:237], v[82:97]
	v_mfma_f32_32x32x16_f16 v[66:81], v[220:223], v[240:243], v[66:81]
	s_waitcnt lgkmcnt(1)
	v_mfma_f32_32x32x16_f16 v[50:65], v[226:229], v[234:237], v[50:65]
	v_mfma_f32_32x32x16_f16 v[34:49], v[226:229], v[240:243], v[34:49]
	s_waitcnt lgkmcnt(0)
	v_mfma_f32_32x32x16_f16 v[18:33], v[230:233], v[234:237], v[18:33]
	v_mfma_f32_32x32x16_f16 v[2:17], v[230:233], v[240:243], v[2:17]
	s_add_i32 s13, s13, 1
	s_cmp_ge_u32 s13, 32
	s_cbranch_scc1 .LBB0_69
	s_cmp_ge_u32 s13, 31
	s_cbranch_scc1 .Lfg_w0_0
	s_waitcnt vmcnt(6)
	s_branch .Lfg_w1_0

.Lfg_stage1:
	ds_read_b128 v[178:181], v130 offset:24576
	ds_read_b128 v[194:197], v132 offset:24576
	ds_read_b128 v[198:201], v132 offset:26624
	ds_read_b128 v[182:185], v130 offset:26624
	ds_read_b128 v[186:189], v130 offset:28672
	ds_read_b128 v[190:193], v130 offset:30720
	s_cmp_ge_u32 s13, 30
	s_cbranch_scc1 .Lfg_nl1
	s_waitcnt lgkmcnt(4)
	v_mfma_f32_32x32x16_f16 v[114:129], v[178:181], v[194:197], v[114:129]
	ds_read_b128 v[216:219], v131 offset:24576
	s_waitcnt lgkmcnt(4)
	s_add_u32 m0, s18, 0x0
	v_mfma_f32_32x32x16_f16 v[98:113], v[178:181], v[198:201], v[98:113]
	global_load_lds_dwordx4 v139, s[14:15]
	ds_read_b128 v[234:237], v133 offset:24576
	s_waitcnt lgkmcnt(4)
	s_add_u32 m0, s18, 0x1000
	v_mfma_f32_32x32x16_f16 v[82:97], v[182:185], v[194:197], v[82:97]
	global_load_lds_dwordx4 v140, s[14:15]
	ds_read_b128 v[240:243], v133 offset:26624
	s_add_u32 m0, s18, 0x2000
	v_mfma_f32_32x32x16_f16 v[66:81], v[182:185], v[198:201], v[66:81]
	global_load_lds_dwordx4 v141, s[14:15]
	ds_read_b128 v[220:223], v131 offset:26624
	s_waitcnt lgkmcnt(5)
	s_add_u32 m0, s18, 0x3000
	v_mfma_f32_32x32x16_f16 v[50:65], v[186:189], v[194:197], v[50:65]
	global_load_lds_dwordx4 v142, s[14:15]
	ds_read_b128 v[226:229], v131 offset:28672
	s_add_u32 m0, s18, 0x4000
	v_mfma_f32_32x32x16_f16 v[34:49], v[186:189], v[198:201], v[34:49]
	global_load_lds_dwordx4 v143, s[16:17]
	ds_read_b128 v[230:233], v131 offset:30720
	s_waitcnt lgkmcnt(6)
	s_add_u32 m0, s18, 0x5000
	v_mfma_f32_32x32x16_f16 v[18:33], v[190:193], v[194:197], v[18:33]
	global_load_lds_dwordx4 v144, s[16:17]
	v_mfma_f32_32x32x16_f16 v[2:17], v[190:193], v[198:201], v[2:17]
	s_add_u32 s14, s14, 64
	s_addc_u32 s15, s15, 0
	s_add_u32 s16, s16, 64
	s_addc_u32 s17, s17, 0
	s_branch .Lfg_dd1
.Lfg_nl1:
	s_waitcnt lgkmcnt(4)
	v_mfma_f32_32x32x16_f16 v[114:129], v[178:181], v[194:197], v[114:129]
	ds_read_b128 v[216:219], v131 offset:24576
	s_waitcnt lgkmcnt(4)
	v_mfma_f32_32x32x16_f16 v[98:113], v[178:181], v[198:201], v[98:113]
	ds_read_b128 v[234:237], v133 offset:24576
	s_waitcnt lgkmcnt(4)
	v_mfma_f32_32x32x16_f16 v[82:97], v[182:185], v[194:197], v[82:97]
	ds_read_b128 v[240:243], v133 offset:26624
	v_mfma_f32_32x32x16_f16 v[66:81], v[182:185], v[198:201], v[66:81]
	ds_read_b128 v[220:223], v131 offset:26624
	s_waitcnt lgkmcnt(5)
	v_mfma_f32_32x32x16_f16 v[50:65], v[186:189], v[194:197], v[50:65]
	ds_read_b128 v[226:229], v131 offset:28672
	v_mfma_f32_32x32x16_f16 v[34:49], v[186:189], v[198:201], v[34:49]
	ds_read_b128 v[230:233], v131 offset:30720
	s_waitcnt lgkmcnt(6)
	v_mfma_f32_32x32x16_f16 v[18:33], v[190:193], v[194:197], v[18:33]
	v_mfma_f32_32x32x16_f16 v[2:17], v[190:193], v[198:201], v[2:17]

.Lfg_stage2:
	ds_read_b128 v[178:181], v130 offset:49152
	ds_read_b128 v[194:197], v132 offset:49152
	ds_read_b128 v[198:201], v132 offset:51200
	ds_read_b128 v[182:185], v130 offset:51200
	ds_read_b128 v[186:189], v130 offset:53248
	ds_read_b128 v[190:193], v130 offset:55296
	s_cmp_ge_u32 s13, 30
	s_cbranch_scc1 .Lfg_nl2
	s_waitcnt lgkmcnt(4)
	v_mfma_f32_32x32x16_f16 v[114:129], v[178:181], v[194:197], v[114:129]
	ds_read_b128 v[216:219], v131 offset:49152
	s_waitcnt lgkmcnt(4)
	s_add_u32 m0, s18, 0x6000
	v_mfma_f32_32x32x16_f16 v[98:113], v[178:181], v[198:201], v[98:113]
	global_load_lds_dwordx4 v139, s[14:15]
	ds_read_b128 v[234:237], v133 offset:49152
	s_waitcnt lgkmcnt(4)
	s_add_u32 m0, s18, 0x7000
	v_mfma_f32_32x32x16_f16 v[82:97], v[182:185], v[194:197], v[82:97]
	global_load_lds_dwordx4 v140, s[14:15]
	ds_read_b128 v[240:243], v133 offset:51200
	s_add_u32 m0, s18, 0x8000
	v_mfma_f32_32x32x16_f16 v[66:81], v[182:185], v[198:201], v[66:81]
	global_load_lds_dwordx4 v141, s[14:15]
	ds_read_b128 v[220:223], v131 offset:51200
	s_waitcnt lgkmcnt(5)
	s_add_u32 m0, s18, 0x9000
	v_mfma_f32_32x32x16_f16 v[50:65], v[186:189], v[194:197], v[50:65]
	global_load_lds_dwordx4 v142, s[14:15]
	ds_read_b128 v[226:229], v131 offset:53248
	s_add_u32 m0, s18, 0xa000
	v_mfma_f32_32x32x16_f16 v[34:49], v[186:189], v[198:201], v[34:49]
	global_load_lds_dwordx4 v143, s[16:17]
	ds_read_b128 v[230:233], v131 offset:55296
	s_waitcnt lgkmcnt(6)
	s_add_u32 m0, s18, 0xb000
	v_mfma_f32_32x32x16_f16 v[18:33], v[190:193], v[194:197], v[18:33]
	global_load_lds_dwordx4 v144, s[16:17]
	v_mfma_f32_32x32x16_f16 v[2:17], v[190:193], v[198:201], v[2:17]
	s_add_u32 s14, s14, 64
	s_addc_u32 s15, s15, 0
	s_add_u32 s16, s16, 64
	s_addc_u32 s17, s17, 0
	s_branch .Lfg_dd2
.Lfg_nl2:
	s_waitcnt lgkmcnt(4)
	v_mfma_f32_32x32x16_f16 v[114:129], v[178:181], v[194:197], v[114:129]
	ds_read_b128 v[216:219], v131 offset:49152
	s_waitcnt lgkmcnt(4)
	v_mfma_f32_32x32x16_f16 v[98:113], v[178:181], v[198:201], v[98:113]
	ds_read_b128 v[234:237], v133 offset:49152
	s_waitcnt lgkmcnt(4)
	v_mfma_f32_32x32x16_f16 v[82:97], v[182:185], v[194:197], v[82:97]
	ds_read_b128 v[240:243], v133 offset:51200
	v_mfma_f32_32x32x16_f16 v[66:81], v[182:185], v[198:201], v[66:81]
	ds_read_b128 v[220:223], v131 offset:51200
	s_waitcnt lgkmcnt(5)
	v_mfma_f32_32x32x16_f16 v[50:65], v[186:189], v[194:197], v[50:65]
	ds_read_b128 v[226:229], v131 offset:53248
	v_mfma_f32_32x32x16_f16 v[34:49], v[186:189], v[198:201], v[34:49]
	ds_read_b128 v[230:233], v131 offset:55296
	s_waitcnt lgkmcnt(6)
	v_mfma_f32_32x32x16_f16 v[18:33], v[190:193], v[194:197], v[18:33]
	v_mfma_f32_32x32x16_f16 v[2:17], v[190:193], v[198:201], v[2:17]

; DI int TIDX() { int t = threadIdx.x; asm volatile("" : "+v"(t)); return t; }
; #define XCD_LOOP_W(Mt, ntn) const int xcd_ = BIDX() & 7; const int Mx_ = ((Mt) + 7) >> 3; for (int u_ = BIDX() >> 3; u_ < Mx_ * (ntn); u_ += (int)(gridDim.x >> 3))
; template <class BR>
; DI void gemm_tile_w(const h16* __restrict__ A, int lda, const h16* __restrict__ B, int ldb, BR brow, int K, f32x16 (&acc)[4][2], h16* sm) {
;   const int tid = TIDX(), lane = tid & 63, w = tid >> 6, wm = w >> 1, wn = w & 1, r = lane & 31, hh = lane >> 5;
;   const unsigned ao = (unsigned)(tid >> 2) * (unsigned)lda + (unsigned)(tid & 3) * 8u;
;   const unsigned bo0 = (unsigned)brow(tid >> 2) * (unsigned)ldb + (unsigned)(tid & 3) * 8u;
;   const unsigned bo1 = (unsigned)brow((tid >> 2) + 64) * (unsigned)ldb + (unsigned)(tid & 3) * 8u;
;   const h16* ag = A;
;   const h16* bg = B;
;   u32x4 ra0[4], rb0[2], ra1[4], rb1[2];
; #pragma unroll
;   for (int i = 0; i < 4; ++i) ra0[i] = *(const u32x4*)(ag + (ao + (unsigned)i * 64u * (unsigned)lda));
;   rb0[0] = *(const u32x4*)(bg + bo0);
;   rb0[1] = *(const u32x4*)(bg + bo1);
;   ag += 32; bg += 32;
; #pragma unroll
;   for (int i = 0; i < 4; ++i) ra1[i] = *(const u32x4*)(ag + (ao + (unsigned)i * 64u * (unsigned)lda));
;   rb1[0] = *(const u32x4*)(bg + bo0);
;   rb1[1] = *(const u32x4*)(bg + bo1);
;   const int nk = K >> 5;
;   const int wofs = (tid >> 2) * LS2 + (tid & 3) * 8;
; DI void phase_proj(const P& p, int l, char* smem) {
;     ...
;   XCD_LOOP_W(136, 27) {
;     int mt_, nt_;
;     tile_map(u_, Mx_, 27, xcd_, mt_, nt_);
;     if (mt_ >= 136) continue;
;     const int m0 = mt_ * 256, n0 = nt_ * 128;
;     f32x16 acc[4][2];
;     zero_acc_w(acc);
;     gemm_tile_w(hbuf + (size_t)m0 * 1024, 1024, W, 1024, [&](int rr) { return n0 + rr; }, 1024, acc, (h16*)smem);
.LBB0_693:
	s_mul_hi_i32 s0, s36, 0x4bda12f7
	s_lshr_b32 s1, s0, 31
	s_ashr_i32 s0, s0, 6
	s_add_i32 s0, s0, s1
	s_lshl_b32 s4, s0, 3
	s_sub_i32 s1, 17, s4
	s_min_u32 s5, s1, 8
	v_cvt_f32_ubyte0_e32 v0, s5
	v_rcp_iflag_f32_e32 v0, v0
	s_sub_i32 s7, 0, s5
	s_mulk_i32 s0, 0xff28
	s_add_i32 s0, s0, s36
	v_mul_f32_e32 v0, 0x4f7ffffe, v0
	v_cvt_u32_f32_e32 v0, v0
	s_abs_i32 s6, s0
	s_ashr_i32 s1, s0, 31
	v_readfirstlane_b32 s8, v0
	s_mul_i32 s7, s7, s8
	s_mul_hi_u32 s7, s8, s7
	s_add_i32 s8, s8, s7
	s_mul_hi_u32 s7, s6, s8
	s_mul_i32 s8, s7, s5
	s_sub_i32 s6, s6, s8
	s_add_i32 s8, s7, 1
	s_sub_i32 s9, s6, s5
	s_cmp_ge_u32 s6, s5
	s_cselect_b32 s7, s8, s7
	s_cselect_b32 s6, s9, s6
	s_add_i32 s8, s7, 1
	s_cmp_ge_u32 s6, s5
	s_cselect_b32 s6, s8, s7
	s_xor_b32 s6, s6, s1
	s_sub_i32 s1, s6, s1
	s_add_i32 s4, s4, s72
	s_mul_i32 s5, s5, s1
	s_add_i32 s4, s4, s0
	s_sub_i32 s0, s4, s5
	s_cmpk_gt_i32 s0, 0x87
	s_cbranch_scc1 .LBB0_692
	s_lshl_b32 s0, s0, 8
	s_lshl_b32 s10, s1, 7
	s_ashr_i32 s1, s0, 31
	v_mov_b32_e32 v14, v203
	s_lshl_b64 s[4:5], s[0:1], 11
	s_add_u32 s4, s69, s4
	v_ashrrev_i32_e32 v15, 2, v14
	v_lshlrev_b32_e32 v0, 3, v14
	v_and_b32_e32 v16, 24, v0
	v_bfe_u32 v17, v14, 4, 2
	v_lshlrev_b32_e32 v17, 3, v17
	v_xor_b32_e32 v16, v16, v17
	v_add_u32_e32 v10, s10, v15
	s_addc_u32 s5, s24, s5
	v_lshl_or_b32 v0, v15, 10, v16
	v_lshl_or_b32 v210, v10, 10, v16
	v_lshl_add_u64 v[2:3], v[0:1], 1, s[4:5]
	v_add_u32_e32 v204, 0x10000, v0
	v_mov_b32_e32 v205, v1
	v_add_u32_e32 v206, 0x20000, v0
	v_mov_b32_e32 v207, v1
	v_add_u32_e32 v208, 0x30000, v0
	v_mov_b32_e32 v209, v1
	v_add_u32_e32 v212, 0x10000, v210
	v_mov_b32_e32 v211, v1
	s_mov_b64 s[6:7], s[54:55]
	v_mov_b32_e32 v213, v1
	v_lshl_add_u64 v[4:5], v[204:205], 1, s[4:5]
	v_lshl_add_u64 v[6:7], v[206:207], 1, s[4:5]
	v_lshl_add_u64 v[8:9], v[208:209], 1, s[4:5]
	v_lshl_add_u64 v[10:11], v[210:211], 1, s[6:7]
	v_lshl_add_u64 v[12:13], v[212:213], 1, s[6:7]
	v_readfirstlane_b32 s18, v203
	s_nop 3
	s_lshr_b32 s18, s18, 6
	s_lshl_b32 s18, s18, 10
	v_and_b32_e32 v136, 31, v203
	v_bfe_u32 v137, v203, 5, 1
	v_bfe_u32 v138, v203, 2, 2
	v_xor_b32_e32 v137, v137, v138
	v_lshlrev_b32_e32 v137, 4, v137
	v_lshl_or_b32 v136, v136, 6, v137
	v_lshrrev_b32_e32 v138, 7, v203
	v_lshl_add_u32 v130, v138, 13, v136
	v_bfe_u32 v138, v203, 6, 1
	v_lshl_add_u32 v132, v138, 12, v136
	v_add_u32_e32 v132, 0x4000, v132
	v_xor_b32_e32 v131, 32, v130
	v_xor_b32_e32 v133, 32, v132
	v_lshlrev_b32_e32 v139, 1, v0
	v_lshlrev_b32_e32 v140, 1, v204
	v_lshlrev_b32_e32 v141, 1, v206
	v_lshlrev_b32_e32 v142, 1, v208
	v_lshlrev_b32_e32 v143, 1, v210
	v_lshlrev_b32_e32 v144, 1, v212
	s_add_u32 m0, s18, 0x0
	s_nop 0
	global_load_lds_dwordx4 v139, s[4:5]
	s_add_u32 m0, s18, 0x1000
	s_nop 0
	global_load_lds_dwordx4 v140, s[4:5]
	s_add_u32 m0, s18, 0x2000
	s_nop 0
	global_load_lds_dwordx4 v141, s[4:5]
	s_add_u32 m0, s18, 0x3000
	s_nop 0
	global_load_lds_dwordx4 v142, s[4:5]
	s_add_u32 m0, s18, 0x4000
	s_nop 0
	global_load_lds_dwordx4 v143, s[6:7]
	s_add_u32 m0, s18, 0x5000
	s_nop 0
	global_load_lds_dwordx4 v144, s[6:7]
	s_add_u32 s4, s4, 64
	s_addc_u32 s5, s5, 0
	s_add_u32 s6, s6, 64
	s_addc_u32 s7, s7, 0
	s_add_u32 m0, s18, 0x6000
	s_nop 0
	global_load_lds_dwordx4 v139, s[4:5]
	s_add_u32 m0, s18, 0x7000
	s_nop 0
	global_load_lds_dwordx4 v140, s[4:5]
	s_add_u32 m0, s18, 0x8000
	s_nop 0
	global_load_lds_dwordx4 v141, s[4:5]
	s_add_u32 m0, s18, 0x9000
	s_nop 0
	global_load_lds_dwordx4 v142, s[4:5]
	s_add_u32 m0, s18, 0xa000
	s_nop 0
	global_load_lds_dwordx4 v143, s[6:7]
	s_add_u32 m0, s18, 0xb000
	s_nop 0
	global_load_lds_dwordx4 v144, s[6:7]
	s_add_u32 s4, s4, 64
	s_addc_u32 s5, s5, 0
	s_add_u32 s6, s6, 64
	s_addc_u32 s7, s7, 0
	v_mov_b32_e32 v114, 0
	s_mov_b32 s1, 0
	v_mov_b32_e32 v115, v114
	v_mov_b32_e32 v116, v114
	s_waitcnt vmcnt(14)
	v_mov_b32_e32 v117, v114
	v_mov_b32_e32 v118, v114
	v_mov_b32_e32 v119, v114
	s_waitcnt vmcnt(13)
	v_mov_b32_e32 v120, v114
	v_mov_b32_e32 v121, v114
	v_mov_b32_e32 v122, v114
	s_waitcnt vmcnt(12)
	v_mov_b32_e32 v123, v114
	v_mov_b32_e32 v124, v114
	v_mov_b32_e32 v125, v114
	v_mov_b32_e32 v126, v114
	v_mov_b32_e32 v127, v114
	v_mov_b32_e32 v128, v114
	v_mov_b32_e32 v129, v114
	v_mov_b32_e32 v98, v114
	v_mov_b32_e32 v99, v114
	v_mov_b32_e32 v100, v114
	v_mov_b32_e32 v101, v114
	v_mov_b32_e32 v102, v114
	v_mov_b32_e32 v103, v114
	v_mov_b32_e32 v104, v114
	v_mov_b32_e32 v105, v114
	v_mov_b32_e32 v106, v114
	v_mov_b32_e32 v107, v114
	v_mov_b32_e32 v108, v114
	v_mov_b32_e32 v109, v114
	v_mov_b32_e32 v110, v114
	v_mov_b32_e32 v111, v114
	v_mov_b32_e32 v112, v114
	v_mov_b32_e32 v113, v114
	v_mov_b32_e32 v82, v114
	v_mov_b32_e32 v83, v114
	v_mov_b32_e32 v84, v114
	v_mov_b32_e32 v85, v114
	v_mov_b32_e32 v86, v114
	v_mov_b32_e32 v87, v114
	v_mov_b32_e32 v88, v114
	v_mov_b32_e32 v89, v114
	v_mov_b32_e32 v90, v114
	v_mov_b32_e32 v91, v114
	v_mov_b32_e32 v92, v114
	v_mov_b32_e32 v93, v114
	v_mov_b32_e32 v94, v114
	v_mov_b32_e32 v95, v114
	v_mov_b32_e32 v96, v114
	v_mov_b32_e32 v97, v114
	v_mov_b32_e32 v66, v114
	v_mov_b32_e32 v67, v114
	v_mov_b32_e32 v68, v114
	v_mov_b32_e32 v69, v114
	v_mov_b32_e32 v70, v114
	v_mov_b32_e32 v71, v114
	v_mov_b32_e32 v72, v114
	v_mov_b32_e32 v73, v114
	v_mov_b32_e32 v74, v114
	v_mov_b32_e32 v75, v114
	v_mov_b32_e32 v76, v114
	v_mov_b32_e32 v77, v114
	v_mov_b32_e32 v78, v114
	v_mov_b32_e32 v79, v114
	v_mov_b32_e32 v80, v114
	v_mov_b32_e32 v81, v114
	v_mov_b32_e32 v50, v114
	v_mov_b32_e32 v51, v114
	v_mov_b32_e32 v52, v114
	v_mov_b32_e32 v53, v114
	v_mov_b32_e32 v54, v114
	v_mov_b32_e32 v55, v114
	v_mov_b32_e32 v56, v114
	v_mov_b32_e32 v57, v114
	v_mov_b32_e32 v58, v114
	v_mov_b32_e32 v59, v114
	v_mov_b32_e32 v60, v114
	v_mov_b32_e32 v61, v114
	v_mov_b32_e32 v62, v114
	v_mov_b32_e32 v63, v114
	v_mov_b32_e32 v64, v114
	v_mov_b32_e32 v65, v114
	v_mov_b32_e32 v34, v114
	v_mov_b32_e32 v35, v114
	v_mov_b32_e32 v36, v114
	v_mov_b32_e32 v37, v114
	v_mov_b32_e32 v38, v114
	v_mov_b32_e32 v39, v114
	v_mov_b32_e32 v40, v114
	v_mov_b32_e32 v41, v114
	v_mov_b32_e32 v42, v114
	v_mov_b32_e32 v43, v114
	v_mov_b32_e32 v44, v114
	v_mov_b32_e32 v45, v114
	v_mov_b32_e32 v46, v114
	v_mov_b32_e32 v47, v114
	v_mov_b32_e32 v48, v114
	v_mov_b32_e32 v49, v114
	v_mov_b32_e32 v18, v114
	v_mov_b32_e32 v19, v114
	v_mov_b32_e32 v20, v114
	v_mov_b32_e32 v21, v114
	v_mov_b32_e32 v22, v114
	v_mov_b32_e32 v23, v114
	v_mov_b32_e32 v24, v114
	v_mov_b32_e32 v25, v114
	v_mov_b32_e32 v26, v114
	v_mov_b32_e32 v27, v114
	v_mov_b32_e32 v28, v114
	v_mov_b32_e32 v29, v114
	v_mov_b32_e32 v30, v114
	v_mov_b32_e32 v31, v114
	v_mov_b32_e32 v32, v114
	v_mov_b32_e32 v33, v114
	v_mov_b32_e32 v2, v114
	v_mov_b32_e32 v3, v114
	v_mov_b32_e32 v4, v114
	v_mov_b32_e32 v5, v114
	v_mov_b32_e32 v6, v114
	v_mov_b32_e32 v7, v114
	v_mov_b32_e32 v8, v114
	v_mov_b32_e32 v9, v114
	v_mov_b32_e32 v10, v114
	v_mov_b32_e32 v11, v114
	v_mov_b32_e32 v12, v114
	v_mov_b32_e32 v13, v114
	v_mov_b32_e32 v14, v114
	v_mov_b32_e32 v15, v114
	v_mov_b32_e32 v16, v114
	v_mov_b32_e32 v17, v114
	s_waitcnt vmcnt(6)
	s_barrier
.Lpg_stage0:
	ds_read_b128 v[178:181], v130 offset:0
	ds_read_b128 v[194:197], v132 offset:0
	ds_read_b128 v[198:201], v132 offset:2048
	ds_read_b128 v[182:185], v130 offset:2048
	ds_read_b128 v[186:189], v130 offset:4096
	ds_read_b128 v[190:193], v130 offset:6144
	s_cmp_ge_u32 s1, 30
	s_cbranch_scc1 .Lpg_nl0
	s_waitcnt lgkmcnt(4)
	v_mfma_f32_32x32x16_f16 v[114:129], v[178:181], v[194:197], v[114:129]
	ds_read_b128 v[216:219], v131 offset:0
	s_waitcnt lgkmcnt(4)
	s_add_u32 m0, s18, 0xc000
	v_mfma_f32_32x32x16_f16 v[98:113], v[178:181], v[198:201], v[98:113]
	global_load_lds_dwordx4 v139, s[4:5]
	ds_read_b128 v[234:237], v133 offset:0
	s_waitcnt lgkmcnt(4)
	s_add_u32 m0, s18, 0xd000
	v_mfma_f32_32x32x16_f16 v[82:97], v[182:185], v[194:197], v[82:97]
	global_load_lds_dwordx4 v140, s[4:5]
	ds_read_b128 v[240:243], v133 offset:2048
	s_add_u32 m0, s18, 0xe000
	v_mfma_f32_32x32x16_f16 v[66:81], v[182:185], v[198:201], v[66:81]
	global_load_lds_dwordx4 v141, s[4:5]
	ds_read_b128 v[220:223], v131 offset:2048
	s_waitcnt lgkmcnt(5)
	s_add_u32 m0, s18, 0xf000
	v_mfma_f32_32x32x16_f16 v[50:65], v[186:189], v[194:197], v[50:65]
	global_load_lds_dwordx4 v142, s[4:5]
	ds_read_b128 v[226:229], v131 offset:4096
	s_add_u32 m0, s18, 0x10000
	v_mfma_f32_32x32x16_f16 v[34:49], v[186:189], v[198:201], v[34:49]
	global_load_lds_dwordx4 v143, s[6:7]
	ds_read_b128 v[230:233], v131 offset:6144
	s_waitcnt lgkmcnt(6)
	s_add_u32 m0, s18, 0x11000
	v_mfma_f32_32x32x16_f16 v[18:33], v[190:193], v[194:197], v[18:33]
	global_load_lds_dwordx4 v144, s[6:7]
	v_mfma_f32_32x32x16_f16 v[2:17], v[190:193], v[198:201], v[2:17]
	s_add_u32 s4, s4, 64
	s_addc_u32 s5, s5, 0
	s_add_u32 s6, s6, 64
	s_addc_u32 s7, s7, 0
	s_branch .Lpg_dd0

; template <class BR>
; DI void gemm_tile_w(const h16* __restrict__ A, int lda, const h16* __restrict__ B, int ldb, BR brow, int K, f32x16 (&acc)[4][2], h16* sm) {
;     ...
;   for (int kt = 0; kt < nk; kt += 2) {
;     WIDE_HALF(ra0, rb0, 0, kt)
;     WIDE_HALF(ra1, rb1, 1, kt + 1)
;   }
.Lpg_dd0:
	s_waitcnt lgkmcnt(4)
	v_mfma_f32_32x32x16_f16 v[114:129], v[216:219], v[234:237], v[114:129]
	s_waitcnt lgkmcnt(3)
	v_mfma_f32_32x32x16_f16 v[98:113], v[216:219], v[240:243], v[98:113]
	s_waitcnt lgkmcnt(2)
	v_mfma_f32_32x32x16_f16 v[82:97], v[220:223], v[234:237], v[82:97]
	v_mfma_f32_32x32x16_f16 v[66:81], v[220:223], v[240:243], v[66:81]
	s_waitcnt lgkmcnt(1)
	v_mfma_f32_32x32x16_f16 v[50:65], v[226:229], v[234:237], v[50:65]
	v_mfma_f32_32x32x16_f16 v[34:49], v[226:229], v[240:243], v[34:49]
	s_waitcnt lgkmcnt(0)
	v_mfma_f32_32x32x16_f16 v[18:33], v[230:233], v[234:237], v[18:33]
	v_mfma_f32_32x32x16_f16 v[2:17], v[230:233], v[240:243], v[2:17]
	s_add_i32 s1, s1, 1
	s_cmp_ge_u32 s1, 32
	s_cbranch_scc1 .LBB0_700
	s_cmp_ge_u32 s1, 31
	s_cbranch_scc1 .Lpg_w0_0
	s_waitcnt vmcnt(6)
	s_branch .Lpg_w1_0

.Lpg_stage1:
	ds_read_b128 v[178:181], v130 offset:24576
	ds_read_b128 v[194:197], v132 offset:24576
	ds_read_b128 v[198:201], v132 offset:26624
	ds_read_b128 v[182:185], v130 offset:26624
	ds_read_b128 v[186:189], v130 offset:28672
	ds_read_b128 v[190:193], v130 offset:30720
	s_cmp_ge_u32 s1, 30
	s_cbranch_scc1 .Lpg_nl1
	s_waitcnt lgkmcnt(4)
	v_mfma_f32_32x32x16_f16 v[114:129], v[178:181], v[194:197], v[114:129]
	ds_read_b128 v[216:219], v131 offset:24576
	s_waitcnt lgkmcnt(4)
	s_add_u32 m0, s18, 0x0
	v_mfma_f32_32x32x16_f16 v[98:113], v[178:181], v[198:201], v[98:113]
	global_load_lds_dwordx4 v139, s[4:5]
	ds_read_b128 v[234:237], v133 offset:24576
	s_waitcnt lgkmcnt(4)
	s_add_u32 m0, s18, 0x1000
	v_mfma_f32_32x32x16_f16 v[82:97], v[182:185], v[194:197], v[82:97]
	global_load_lds_dwordx4 v140, s[4:5]
	ds_read_b128 v[240:243], v133 offset:26624
	s_add_u32 m0, s18, 0x2000
	v_mfma_f32_32x32x16_f16 v[66:81], v[182:185], v[198:201], v[66:81]
	global_load_lds_dwordx4 v141, s[4:5]
	ds_read_b128 v[220:223], v131 offset:26624
	s_waitcnt lgkmcnt(5)
	s_add_u32 m0, s18, 0x3000
	v_mfma_f32_32x32x16_f16 v[50:65], v[186:189], v[194:197], v[50:65]
	global_load_lds_dwordx4 v142, s[4:5]
	ds_read_b128 v[226:229], v131 offset:28672
	s_add_u32 m0, s18, 0x4000
	v_mfma_f32_32x32x16_f16 v[34:49], v[186:189], v[198:201], v[34:49]
	global_load_lds_dwordx4 v143, s[6:7]
	ds_read_b128 v[230:233], v131 offset:30720
	s_waitcnt lgkmcnt(6)
	s_add_u32 m0, s18, 0x5000
	v_mfma_f32_32x32x16_f16 v[18:33], v[190:193], v[194:197], v[18:33]
	global_load_lds_dwordx4 v144, s[6:7]
	v_mfma_f32_32x32x16_f16 v[2:17], v[190:193], v[198:201], v[2:17]
	s_add_u32 s4, s4, 64
	s_addc_u32 s5, s5, 0
	s_add_u32 s6, s6, 64
	s_addc_u32 s7, s7, 0
	s_branch .Lpg_dd1

.Lpg_stage2:
	ds_read_b128 v[178:181], v130 offset:49152
	ds_read_b128 v[194:197], v132 offset:49152
	ds_read_b128 v[198:201], v132 offset:51200
	ds_read_b128 v[182:185], v130 offset:51200
	ds_read_b128 v[186:189], v130 offset:53248
	ds_read_b128 v[190:193], v130 offset:55296
	s_cmp_ge_u32 s1, 30
	s_cbranch_scc1 .Lpg_nl2
	s_waitcnt lgkmcnt(4)
	v_mfma_f32_32x32x16_f16 v[114:129], v[178:181], v[194:197], v[114:129]
	ds_read_b128 v[216:219], v131 offset:49152
	s_waitcnt lgkmcnt(4)
	s_add_u32 m0, s18, 0x6000
	v_mfma_f32_32x32x16_f16 v[98:113], v[178:181], v[198:201], v[98:113]
	global_load_lds_dwordx4 v139, s[4:5]
	ds_read_b128 v[234:237], v133 offset:49152
	s_waitcnt lgkmcnt(4)
	s_add_u32 m0, s18, 0x7000
	v_mfma_f32_32x32x16_f16 v[82:97], v[182:185], v[194:197], v[82:97]
	global_load_lds_dwordx4 v140, s[4:5]
	ds_read_b128 v[240:243], v133 offset:51200
	s_add_u32 m0, s18, 0x8000
	v_mfma_f32_32x32x16_f16 v[66:81], v[182:185], v[198:201], v[66:81]
	global_load_lds_dwordx4 v141, s[4:5]
	ds_read_b128 v[220:223], v131 offset:51200
	s_waitcnt lgkmcnt(5)
	s_add_u32 m0, s18, 0x9000
	v_mfma_f32_32x32x16_f16 v[50:65], v[186:189], v[194:197], v[50:65]
	global_load_lds_dwordx4 v142, s[4:5]
	ds_read_b128 v[226:229], v131 offset:53248
	s_add_u32 m0, s18, 0xa000
	v_mfma_f32_32x32x16_f16 v[34:49], v[186:189], v[198:201], v[34:49]
	global_load_lds_dwordx4 v143, s[6:7]
	ds_read_b128 v[230:233], v131 offset:55296
	s_waitcnt lgkmcnt(6)
	s_add_u32 m0, s18, 0xb000
	v_mfma_f32_32x32x16_f16 v[18:33], v[190:193], v[194:197], v[18:33]
	global_load_lds_dwordx4 v144, s[6:7]
	v_mfma_f32_32x32x16_f16 v[2:17], v[190:193], v[198:201], v[2:17]
	s_add_u32 s4, s4, 64
	s_addc_u32 s5, s5, 0
	s_add_u32 s6, s6, 64
	s_addc_u32 s7, s7, 0
	s_branch .Lpg_dd2
